# MLA loop: K tiles fetched two key tiles ahead via running offsets, counted vmcnt at the LDS store points
# baseline (speedup 1.0000x reference)
; #define MFMA(a, b, c) __builtin_amdgcn_mfma_f32_32x32x16_bf16((a), (b), (c), 0, 0, 0)
; template <int DQK>
; DI void attn_tile(const u16* __restrict__ q, int ldq, int qpos0, const Seg& s0, const Seg& s1, int nseg, bool has_sink,
;                   float sinkl2, u16* __restrict__ out, int ldo, char* lds) {
;     ...
;   auto compute = [&](int i) {
;     const Seg& sg = (i < nt0) ? s0 : s1;
;     const int off = ((i < nt0) ? i : i - nt0) << 6;
;     f32x16 sa = zero16(), sb = zero16();
; #pragma unroll
;     for (int ks = 0; ks < NKS; ++ks) {
;       bf16x8 a0 = *(const bf16x8*)(Ks + r * KST + ks * 16 + 8 * h);
;       bf16x8 a1 = *(const bf16x8*)(Ks + (32 + r) * KST + ks * 16 + 8 * h);
;       sa = MFMA(a0, qf[ks], sa);
;       sb = MFMA(a1, qf[ks], sb);
;     }
;     ...
;   ATT_LOADX(0, kreg0, kreg1, vreg0);
;   ATT_LOADX(1, krgB0, krgB1, vrgB0);
;   for (int i = 0; i < NT; i += 2) {
;     __syncthreads();
;     ATT_STOREX(kreg0, kreg1, vreg0);
;     __syncthreads();
;     if (i + 2 < NT) ATT_LOADX(i + 2, kreg0, kreg1, vreg0);
;     compute(i);
.LBB0_599:
	s_or_b64 exec, exec, s[4:5]
	v_add_u32_e32 v4, 64, v117
	v_mov_b64_e32 v[2:3], s[12:13]
	v_mad_i64_i32 v[2:3], s[2:3], v4, s61, v[2:3]
	v_lshl_add_u64 v[2:3], v[2:3], 0, v[0:1]
	global_load_dwordx4 v[110:113], v[2:3], off offset:128
	v_subrev_u32_e32 v235, s84, v2
	v_add_u32_e32 v235, 128, v235
	s_movk_i32 s4, 0xd0
	v_lshlrev_b32_e32 v5, 1, v10
	v_lshlrev_b32_e32 v114, 2, v8
	v_lshrrev_b32_e32 v2, 2, v7
	v_mad_u32_u24 v130, v6, s4, v5
	v_and_b32_e32 v6, 64, v209
	v_and_or_b32 v2, v2, 3, v114
	s_add_u32 s23, s12, 0x80
	v_mul_lo_u32 v4, v116, s4
	v_xor_b32_e32 v5, 32, v209
	v_add_u32_e32 v6, 64, v6
	v_mul_u32_u24_e32 v2, 0xc0, v2
	v_lshlrev_b32_e32 v3, 1, v7
	s_addc_u32 s24, s13, 0
	v_lshl_add_u32 v121, v118, 1, v4
	v_mul_lo_u32 v4, v120, s4
	s_movk_i32 s2, 0xc0
	v_cmp_lt_i32_e64 s[4:5], v5, v6
	v_and_or_b32 v2, v3, 32, v2
	v_and_b32_e32 v3, 24, v11
	s_add_u32 s25, s8, 0x80
	v_lshl_add_u32 v129, v122, 1, v4
	v_mul_lo_u32 v4, v117, s2
	v_cndmask_b32_e64 v5, v209, v5, s[4:5]
	v_mov_b32_e32 v128, 0
	s_mov_b32 s22, 3
	s_addc_u32 s26, s9, 0
	v_ashrrev_i32_e32 v123, 31, v122
	v_mov_b32_e32 v124, v118
	v_mov_b32_e32 v125, v1
	v_cmp_lt_i32_e64 s[2:3], 7, v9
	v_mov_b32_e32 v126, v122
	v_mov_b32_e32 v127, v1
	v_lshlrev_b32_e32 v131, 2, v5
	v_mov_b32_e32 v134, 0xf149f2ca
	v_add_u32_e32 v132, v0, v4
	v_add_u32_e32 v133, v2, v3
	v_mov_b32_e32 v2, 0
	v_mov_b32_e32 v3, v128
	v_mov_b32_e32 v4, v128
	v_mov_b32_e32 v5, v128
	v_mov_b32_e32 v6, v128
	v_mov_b32_e32 v7, v128
	v_mov_b32_e32 v8, v128
	v_mov_b32_e32 v9, v128
	v_mov_b32_e32 v10, v128
	v_mov_b32_e32 v11, v128
	v_mov_b32_e32 v12, v128
	v_mov_b32_e32 v13, v128
	v_mov_b32_e32 v14, v128
	v_mov_b32_e32 v15, v128
	v_mov_b32_e32 v16, v128
	v_mov_b32_e32 v17, v128
	v_mov_b32_e32 v18, 0
	v_mov_b32_e32 v19, v128
	v_mov_b32_e32 v20, v128
	v_mov_b32_e32 v21, v128
	v_mov_b32_e32 v22, v128
	v_mov_b32_e32 v23, v128
	v_mov_b32_e32 v24, v128
	v_mov_b32_e32 v25, v128
	v_mov_b32_e32 v26, v128
	v_mov_b32_e32 v27, v128
	v_mov_b32_e32 v28, v128
	v_mov_b32_e32 v29, v128
	v_mov_b32_e32 v30, v128
	v_mov_b32_e32 v31, v128
	v_mov_b32_e32 v32, v128
	v_mov_b32_e32 v33, v128
	v_sub_u32_e32 v236, v208, v138
	v_lshlrev_b32_e32 v236, 1, v236
	v_sub_u32_e32 v237, v234, v142
	v_lshlrev_b32_e32 v237, 1, v237
	s_waitcnt vmcnt(0)
	s_barrier
	ds_write_b128 v121, v[90:93]
	s_and_saveexec_b64 s[4:5], s[0:1]
	ds_write_b128 v129, v[94:97]
	s_or_b64 exec, exec, s[4:5]
	s_waitcnt lgkmcnt(0)
	s_barrier
	v_add_u32_e32 v138, v138, v236
	v_add_u32_e32 v142, v142, v237
	global_load_dwordx4 v[90:93], v138, s[84:85]
	s_and_saveexec_b64 s[4:5], s[0:1]
	global_load_dwordx4 v[94:97], v142, s[84:85]
	s_or_b64 exec, exec, s[4:5]
	ds_read_b128 v[34:37], v130
	ds_read_b128 v[38:41], v130 offset:6656
	ds_read_b128 v[42:45], v130 offset:32
	s_waitcnt lgkmcnt(2)
	v_mfma_f32_32x32x16_bf16 v[50:65], v[34:37], v[66:69], 0
	ds_read_b128 v[34:37], v130 offset:6688
	s_waitcnt lgkmcnt(2)
	v_mfma_f32_32x32x16_bf16 v[218:233], v[38:41], v[66:69], 0
	ds_read_b128 v[38:41], v130 offset:64
	s_waitcnt lgkmcnt(2)
	v_mfma_f32_32x32x16_bf16 v[50:65], v[42:45], v[70:73], v[50:65]
	ds_read_b128 v[42:45], v130 offset:6720
	s_waitcnt lgkmcnt(2)
	v_mfma_f32_32x32x16_bf16 v[218:233], v[34:37], v[70:73], v[218:233]
	ds_read_b128 v[34:37], v130 offset:96
	s_waitcnt lgkmcnt(2)
	v_mfma_f32_32x32x16_bf16 v[50:65], v[38:41], v[74:77], v[50:65]
	ds_read_b128 v[38:41], v130 offset:6752
	s_waitcnt lgkmcnt(2)
	v_mfma_f32_32x32x16_bf16 v[218:233], v[42:45], v[74:77], v[218:233]
	ds_read_b128 v[42:45], v130 offset:128
	s_waitcnt lgkmcnt(2)
	v_mfma_f32_32x32x16_bf16 v[50:65], v[34:37], v[78:81], v[50:65]
	ds_read_b128 v[34:37], v130 offset:6784
	s_waitcnt lgkmcnt(2)
	v_mfma_f32_32x32x16_bf16 v[218:233], v[38:41], v[78:81], v[218:233]
	ds_read_b128 v[38:41], v130 offset:160
	s_waitcnt lgkmcnt(2)
	v_mfma_f32_32x32x16_bf16 v[50:65], v[42:45], v[82:85], v[50:65]
	ds_read_b128 v[42:45], v130 offset:6816
	s_waitcnt lgkmcnt(2)
	v_mfma_f32_32x32x16_bf16 v[218:233], v[34:37], v[82:85], v[218:233]
	s_waitcnt lgkmcnt(1)
	v_mfma_f32_32x32x16_bf16 v[50:65], v[38:41], v[86:89], v[50:65]
	s_waitcnt lgkmcnt(0)
	v_mfma_f32_32x32x16_bf16 v[218:233], v[42:45], v[86:89], v[218:233]
	s_branch .LBB0_603

; template <int DQK>
; DI void attn_tile(const u16* __restrict__ q, int ldq, int qpos0, const Seg& s0, const Seg& s1, int nseg, bool has_sink,
;                   float sinkl2, u16* __restrict__ out, int ldo, char* lds) {
;     ...
;     __syncthreads();
;     ATT_STOREX(krgB0, krgB1, vrgB0);
;     __syncthreads();
;     if (i + 3 < NT) ATT_LOADX(i + 3, krgB0, krgB1, vrgB0);
.LBB0_603:
	s_nop 0
	s_cmp_eq_u64 s[0:1], 0
	s_cbranch_scc1 .Lmla_w2a
	s_waitcnt vmcnt(3)
	s_branch .Lmla_w3a

; #define MFMA(a, b, c) __builtin_amdgcn_mfma_f32_32x32x16_bf16((a), (b), (c), 0, 0, 0)
; DI int crow(int reg, int h) { return (reg & 3) + 8 * (reg >> 2) + 4 * h; }
; template <int DQK>
; DI void attn_tile(const u16* __restrict__ q, int ldq, int qpos0, const Seg& s0, const Seg& s1, int nseg, bool has_sink,
;                   float sinkl2, u16* __restrict__ out, int ldo, char* lds) {
;     ...
;   auto compute = [&](int i) {
;     const Seg& sg = (i < nt0) ? s0 : s1;
;     const int off = ((i < nt0) ? i : i - nt0) << 6;
;     f32x16 sa = zero16(), sb = zero16();
; #pragma unroll
;     for (int ks = 0; ks < NKS; ++ks) {
;       bf16x8 a0 = *(const bf16x8*)(Ks + r * KST + ks * 16 + 8 * h);
;       bf16x8 a1 = *(const bf16x8*)(Ks + (32 + r) * KST + ks * 16 + 8 * h);
;       sa = MFMA(a0, qf[ks], sa);
;       sb = MFMA(a1, qf[ks], sb);
;     }
;     if (sg.masked) {
;       const int qpos = qpos0 + qi;
;       const int kb = sg.pos0 + off;
; #pragma unroll
;       for (int g = 0; g < 16; ++g) {
;         int d0 = kb + crow(g, h) - qpos, d1 = d0 + 32;
;         if (d0 > 128 || d0 < -128) sa[g] = -INFINITY;
;         if (d1 > 128 || d1 < -128) sb[g] = -INFINITY;
;       }
;     }
;     float mx = sa[0];
; #pragma unroll
;     for (int g = 1; g < 16; ++g) mx = fmaxf(mx, sa[g]);
; #pragma unroll
;     for (int g = 0; g < 16; ++g) mx = fmaxf(mx, sb[g]);
;     mx = fmaxf(mx, __shfl_xor(mx, 32));
;     const float mn = fmaxf(m, mx);
;     const float alpha = __builtin_amdgcn_exp2f(m - mn);
;     m = mn;
;     float ps = 0.f;
; #pragma unroll
;     for (int g = 0; g < 16; ++g) { sa[g] = __builtin_amdgcn_exp2f(sa[g] - mn); ps += sa[g]; }
; #pragma unroll
;     for (int g = 0; g < 16; ++g) { sb[g] = __builtin_amdgcn_exp2f(sb[g] - mn); ps += sb[g]; }
;     l = l * alpha + ps;
;     ...
;     __syncthreads();
;     ATT_STOREX(krgB0, krgB1, vrgB0);
;     __syncthreads();
;     if (i + 3 < NT) ATT_LOADX(i + 3, krgB0, krgB1, vrgB0);
;     compute(i + 1);
.Lmla_w3a:
	ds_write_b128 v121, v[98:101] offset:32768
	s_and_saveexec_b64 s[4:5], s[0:1]
	ds_write_b128 v129, v[106:109] offset:32768
	s_or_b64 exec, exec, s[4:5]
	s_add_i32 s27, s22, -3
	s_cmpk_gt_u32 s27, 0x41
	s_nop 0
	ds_write_b128 v132, v[102:105] offset:13312
	s_waitcnt lgkmcnt(0)
	s_barrier
	s_cbranch_scc1 .LBB0_617
	s_cmp_eq_u32 s27, 62
	s_cbranch_scc0 .Lmla_e_noswk
	s_sub_u32 s16, s10, s14
	s_lshr_b32 s16, s16, 6
	s_sub_u32 s16, s16, 0x1000
	v_lshrrev_b32_e32 v34, 7, v236
	v_mul_lo_u32 v34, v34, s16
	v_add_u32_e32 v208, v208, v34
	v_lshrrev_b32_e32 v34, 7, v237
	v_mul_lo_u32 v34, v34, s16
	v_add_u32_e32 v234, v234, v34
.Lmla_e_noswk:
	s_cmp_eq_u32 s27, 62
	s_cbranch_scc0 .Lmla_e_noswv
	s_sub_u32 s16, s10, s14
	s_lshr_b32 s16, s16, 6
	s_sub_u32 s16, s16, 0x1000
	s_mul_i32 s17, s16, 0x480
	v_add_u32_e32 v143, s17, v143
.Lmla_e_noswv:
	v_add_u32_e32 v208, v208, v236
	v_add_u32_e32 v234, v234, v237
	v_add_u32_e32 v143, 0x24000, v143
	global_load_dwordx4 v[98:101], v208, s[84:85]
	s_and_saveexec_b64 s[16:17], s[0:1]
	global_load_dwordx4 v[106:109], v234, s[84:85]
	s_or_b64 exec, exec, s[16:17]
	global_load_dwordx4 v[102:105], v143, s[84:85]
.LBB0_617:
	ds_read_b128 v[34:37], v130 offset:32768
	ds_read_b128 v[38:41], v130 offset:39424
	ds_read_b128 v[42:45], v130 offset:32800
	s_waitcnt lgkmcnt(2)
	v_mfma_f32_32x32x16_bf16 v[184:199], v[34:37], v[66:69], 0
	ds_read_b128 v[34:37], v130 offset:39456
	v_max3_f32 v137, v50, v51, v52
	v_max3_f32 v137, v137, v53, v54
	v_max3_f32 v137, v137, v55, v56
	v_max3_f32 v137, v137, v57, v58
	s_waitcnt lgkmcnt(2)
	v_mfma_f32_32x32x16_bf16 v[146:161], v[38:41], v[66:69], 0
	ds_read_b128 v[38:41], v130 offset:32832
	v_max3_f32 v137, v137, v59, v60
	v_max3_f32 v137, v137, v61, v62
	v_max3_f32 v137, v137, v63, v64
	v_max3_f32 v137, v137, v65, v218
	s_waitcnt lgkmcnt(2)
	v_mfma_f32_32x32x16_bf16 v[184:199], v[42:45], v[70:73], v[184:199]
	ds_read_b128 v[42:45], v130 offset:39488
	v_max3_f32 v137, v137, v219, v220
	v_max3_f32 v137, v137, v221, v222
	v_max3_f32 v137, v137, v223, v224
	v_max3_f32 v137, v137, v225, v226
	s_waitcnt lgkmcnt(2)
	v_mfma_f32_32x32x16_bf16 v[146:161], v[34:37], v[70:73], v[146:161]
	ds_read_b128 v[34:37], v130 offset:32864
	v_max3_f32 v137, v137, v227, v228
	v_max3_f32 v137, v137, v229, v230
	v_max3_f32 v137, v137, v231, v232
	v_max3_f32 v137, v137, v233, v233
	s_waitcnt lgkmcnt(2)
	v_mfma_f32_32x32x16_bf16 v[184:199], v[38:41], v[74:77], v[184:199]
	ds_read_b128 v[38:41], v130 offset:39520
	ds_bpermute_b32 v139, v131, v137
	s_waitcnt lgkmcnt(0)
	v_max3_f32 v135, v134, v137, v139
	v_sub_f32_e32 v141, v134, v135
	v_mfma_f32_32x32x16_bf16 v[146:161], v[42:45], v[74:77], v[146:161]
	ds_read_b128 v[42:45], v130 offset:32896
	v_exp_f32_e32 v140, v141
	v_mov_b32_e32 v144, v135
	v_mov_b32_e32 v145, v135
	v_sub_f32_e32 v50, v50, v135
	v_mfma_f32_32x32x16_bf16 v[184:199], v[34:37], v[78:81], v[184:199]
	ds_read_b128 v[34:37], v130 offset:39552
	v_sub_f32_e32 v51, v51, v135
	v_sub_f32_e32 v52, v52, v135
	v_sub_f32_e32 v53, v53, v135
	v_sub_f32_e32 v54, v54, v135
	v_mfma_f32_32x32x16_bf16 v[146:161], v[38:41], v[78:81], v[146:161]
	ds_read_b128 v[38:41], v130 offset:32928
	v_sub_f32_e32 v55, v55, v135
	v_sub_f32_e32 v56, v56, v135
	v_sub_f32_e32 v57, v57, v135
	v_exp_f32_e32 v50, v50
	s_waitcnt lgkmcnt(2)
	v_mfma_f32_32x32x16_bf16 v[184:199], v[42:45], v[82:85], v[184:199]
	ds_read_b128 v[42:45], v130 offset:39584
	v_sub_f32_e32 v58, v58, v135
	v_sub_f32_e32 v59, v59, v135
	v_sub_f32_e32 v60, v60, v135
	v_sub_f32_e32 v61, v61, v135
	s_waitcnt lgkmcnt(2)
	v_mfma_f32_32x32x16_bf16 v[146:161], v[34:37], v[82:85], v[146:161]
	v_exp_f32_e32 v51, v51
	v_sub_f32_e32 v62, v62, v135
	v_sub_f32_e32 v63, v63, v135
	v_sub_f32_e32 v64, v64, v135
	s_waitcnt lgkmcnt(1)
	v_mfma_f32_32x32x16_bf16 v[184:199], v[38:41], v[86:89], v[184:199]
	v_sub_f32_e32 v65, v65, v135
	v_exp_f32_e32 v52, v52
	v_sub_f32_e32 v218, v218, v135
	v_sub_f32_e32 v219, v219, v135
	s_waitcnt lgkmcnt(0)
; #define MFMA(a, b, c) __builtin_amdgcn_mfma_f32_32x32x16_bf16((a), (b), (c), 0, 0, 0)
; #define ATT_VTR(p) __builtin_bit_cast(s16x4, __builtin_amdgcn_ds_read_tr16_b64_v4i16((__attribute__((address_space(3))) v4i16_t*)(p)))
; template <int DQK>
; DI void attn_tile(const u16* __restrict__ q, int ldq, int qpos0, const Seg& s0, const Seg& s1, int nseg, bool has_sink,
;                   float sinkl2, u16* __restrict__ out, int ldo, char* lds) {
;     ...
;     mx = fmaxf(mx, __shfl_xor(mx, 32));
;     const float mn = fmaxf(m, mx);
;     const float alpha = __builtin_amdgcn_exp2f(m - mn);
;     m = mn;
;     float ps = 0.f;
; #pragma unroll
;     for (int g = 0; g < 16; ++g) { sa[g] = __builtin_amdgcn_exp2f(sa[g] - mn); ps += sa[g]; }
; #pragma unroll
;     for (int g = 0; g < 16; ++g) { sb[g] = __builtin_amdgcn_exp2f(sb[g] - mn); ps += sb[g]; }
;     l = l * alpha + ps;
; #pragma unroll
;     for (int g = 0; g < 16; ++g) { o0[g] *= alpha; o1[g] *= alpha; }
; #pragma unroll
;     for (int kt = 0; kt < 2; ++kt) {
; #pragma unroll
;       for (int s = 0; s < 2; ++s) {
;         const f32x16& sv = kt == 0 ? sa : sb;
;         uint4 pu;
;         pu.x = pack2(sv[8 * s + 0], sv[8 * s + 1]); pu.y = pack2(sv[8 * s + 2], sv[8 * s + 3]);
;         pu.z = pack2(sv[8 * s + 4], sv[8 * s + 5]); pu.w = pack2(sv[8 * s + 6], sv[8 * s + 7]);
;         bf16x8 pf = __builtin_bit_cast(bf16x8, pu);
;         const lds_cptr vp = vp0 + (kt * 32 + 16 * s) * (VST * 2);
;         {
;           s16x4 lo = ATT_VTR(vp);
;           s16x4 hi = ATT_VTR(vp + 8 * VST * 2);
;           bf16x8 vf = __builtin_shufflevector(lo, hi, 0, 1, 2, 3, 4, 5, 6, 7);
;           o0 = MFMA(vf, pf, o0);
;         }
;         {
;           s16x4 lo = ATT_VTR(vp + 64);
;           s16x4 hi = ATT_VTR(vp + 8 * VST * 2 + 64);
;           bf16x8 vf = __builtin_shufflevector(lo, hi, 0, 1, 2, 3, 4, 5, 6, 7);
;           o1 = MFMA(vf, pf, o1);
;         }
;       }
;     }
	v_mfma_f32_32x32x16_bf16 v[146:161], v[42:45], v[86:89], v[146:161]
	ds_read_b64_tr_b16 v[46:47], v133 offset:13312
	ds_read_b64_tr_b16 v[48:49], v133 offset:14848
	ds_read_b64_tr_b16 v[200:201], v133 offset:13376
	ds_read_b64_tr_b16 v[202:203], v133 offset:14912
	ds_read_b64_tr_b16 v[204:205], v133 offset:16384
	ds_read_b64_tr_b16 v[206:207], v133 offset:17920
	v_sub_f32_e32 v220, v220, v135
	v_sub_f32_e32 v221, v221, v135
	v_exp_f32_e32 v53, v53
	v_sub_f32_e32 v222, v222, v135
	v_sub_f32_e32 v223, v223, v135
	v_sub_f32_e32 v224, v224, v135
	v_sub_f32_e32 v225, v225, v135
	v_exp_f32_e32 v54, v54
	v_mul_f32_e32 v33, v140, v33
	v_mul_f32_e32 v32, v140, v32
	v_mul_f32_e32 v31, v140, v31
	v_mul_f32_e32 v30, v140, v30
	v_exp_f32_e32 v55, v55
	v_mul_f32_e32 v29, v140, v29
	v_mul_f32_e32 v28, v140, v28
	v_mul_f32_e32 v27, v140, v27
	v_mul_f32_e32 v26, v140, v26
	v_exp_f32_e32 v56, v56
	v_mul_f32_e32 v25, v140, v25
	v_mul_f32_e32 v24, v140, v24
	v_mul_f32_e32 v23, v140, v23
	v_mul_f32_e32 v22, v140, v22
	v_exp_f32_e32 v57, v57
	v_mul_f32_e32 v21, v140, v21
	v_mul_f32_e32 v20, v140, v20
	v_mul_f32_e32 v19, v140, v19
	v_mul_f32_e32 v18, v140, v18
	v_exp_f32_e32 v58, v58
	v_sub_f32_e32 v226, v226, v135
	v_sub_f32_e32 v227, v227, v135
	v_sub_f32_e32 v228, v228, v135
	v_sub_f32_e32 v229, v229, v135
	v_sub_f32_e32 v230, v230, v135
	v_exp_f32_e32 v59, v59
	v_sub_f32_e32 v231, v231, v135
	v_sub_f32_e32 v232, v232, v135
	v_sub_f32_e32 v233, v233, v135
	v_mul_f32_e32 v17, v140, v17
	v_mul_f32_e32 v16, v140, v16
	v_exp_f32_e32 v60, v60
	v_mul_f32_e32 v15, v140, v15
	v_mul_f32_e32 v14, v140, v14
	v_mul_f32_e32 v13, v140, v13
	v_mul_f32_e32 v12, v140, v12
	v_mul_f32_e32 v11, v140, v11
	v_exp_f32_e32 v61, v61
	v_mul_f32_e32 v10, v140, v10
	v_mul_f32_e32 v9, v140, v9
	v_mul_f32_e32 v8, v140, v8
	v_mul_f32_e32 v7, v140, v7
	v_mul_f32_e32 v6, v140, v6
	v_exp_f32_e32 v62, v62
	v_mul_f32_e32 v5, v140, v5
	v_mul_f32_e32 v4, v140, v4
	v_mul_f32_e32 v3, v140, v3
	v_mul_f32_e32 v2, v140, v2
	v_add_f32_e32 v238, v50, v51
	v_exp_f32_e32 v63, v63
	v_add_f32_e32 v238, v238, v52
	v_add_f32_e32 v238, v238, v53
	v_add_f32_e32 v238, v238, v54
	v_add_f32_e32 v238, v238, v55
	v_add_f32_e32 v238, v238, v56
	v_exp_f32_e32 v64, v64
	v_add_f32_e32 v238, v238, v57
	v_cvt_pk_bf16_f32 v50, v50, v51
	v_cvt_pk_bf16_f32 v51, v52, v53
	v_cvt_pk_bf16_f32 v52, v54, v55
	v_cvt_pk_bf16_f32 v53, v56, v57
	v_exp_f32_e32 v65, v65
	s_nop 0
	s_waitcnt lgkmcnt(4)
	v_mfma_f32_32x32x16_bf16 v[18:33], v[46:49], v[50:53], v[18:33]
	ds_read_b64_tr_b16 v[46:47], v133 offset:16448
	ds_read_b64_tr_b16 v[48:49], v133 offset:17984
	s_waitcnt lgkmcnt(4)
	v_mfma_f32_32x32x16_bf16 v[2:17], v[200:203], v[50:53], v[2:17]
	ds_read_b64_tr_b16 v[200:201], v133 offset:19456
	ds_read_b64_tr_b16 v[202:203], v133 offset:20992
	v_exp_f32_e32 v218, v218
	v_add_f32_e32 v238, v238, v58
	v_add_f32_e32 v238, v238, v59
	v_exp_f32_e32 v219, v219
	v_add_f32_e32 v238, v238, v60
	v_add_f32_e32 v238, v238, v61
	v_exp_f32_e32 v220, v220
	v_add_f32_e32 v238, v238, v62
	v_add_f32_e32 v238, v238, v63
	v_exp_f32_e32 v221, v221
	v_add_f32_e32 v238, v238, v64
	v_add_f32_e32 v238, v238, v65
	v_exp_f32_e32 v222, v222
	v_cvt_pk_bf16_f32 v54, v58, v59
	v_cvt_pk_bf16_f32 v55, v60, v61
	v_exp_f32_e32 v223, v223
	v_cvt_pk_bf16_f32 v56, v62, v63
	v_cvt_pk_bf16_f32 v57, v64, v65
	v_exp_f32_e32 v224, v224
	v_exp_f32_e32 v225, v225
	s_nop 0
	s_waitcnt lgkmcnt(4)
	v_mfma_f32_32x32x16_bf16 v[18:33], v[204:207], v[54:57], v[18:33]
	ds_read_b64_tr_b16 v[204:205], v133 offset:19520
	ds_read_b64_tr_b16 v[206:207], v133 offset:21056
	s_waitcnt lgkmcnt(4)
	v_mfma_f32_32x32x16_bf16 v[2:17], v[46:49], v[54:57], v[2:17]
	ds_read_b64_tr_b16 v[46:47], v133 offset:22528
	ds_read_b64_tr_b16 v[48:49], v133 offset:24064
	v_exp_f32_e32 v226, v226
	v_add_f32_e32 v238, v238, v218
	v_add_f32_e32 v238, v238, v219
	v_exp_f32_e32 v227, v227
	v_add_f32_e32 v238, v238, v220
	v_add_f32_e32 v238, v238, v221
	v_exp_f32_e32 v228, v228
	v_add_f32_e32 v238, v238, v222
	v_add_f32_e32 v238, v238, v223
	v_exp_f32_e32 v229, v229
	v_add_f32_e32 v238, v238, v224
	v_add_f32_e32 v238, v238, v225
	v_exp_f32_e32 v230, v230
	v_cvt_pk_bf16_f32 v218, v218, v219
	v_cvt_pk_bf16_f32 v219, v220, v221
	v_exp_f32_e32 v231, v231
	v_cvt_pk_bf16_f32 v220, v222, v223
	v_cvt_pk_bf16_f32 v221, v224, v225
	v_exp_f32_e32 v232, v232
	v_exp_f32_e32 v233, v233
	s_nop 0
	s_waitcnt lgkmcnt(4)
	v_mfma_f32_32x32x16_bf16 v[18:33], v[200:203], v[218:221], v[18:33]
	ds_read_b64_tr_b16 v[200:201], v133 offset:22592
	ds_read_b64_tr_b16 v[202:203], v133 offset:24128
	s_waitcnt lgkmcnt(4)
	v_mfma_f32_32x32x16_bf16 v[2:17], v[204:207], v[218:221], v[2:17]
	v_add_f32_e32 v238, v238, v226
	v_add_f32_e32 v238, v238, v227
	v_add_f32_e32 v238, v238, v228
	v_add_f32_e32 v238, v238, v229
	v_add_f32_e32 v238, v238, v230
	v_add_f32_e32 v238, v238, v231
	v_add_f32_e32 v238, v238, v232
	v_add_f32_e32 v238, v238, v233
	v_cvt_pk_bf16_f32 v222, v226, v227
	v_cvt_pk_bf16_f32 v223, v228, v229
	v_cvt_pk_bf16_f32 v224, v230, v231
	v_cvt_pk_bf16_f32 v225, v232, v233
	s_nop 0
	s_waitcnt lgkmcnt(2)
	v_mfma_f32_32x32x16_bf16 v[18:33], v[46:49], v[222:225], v[18:33]
	s_waitcnt lgkmcnt(0)
	v_mfma_f32_32x32x16_bf16 v[2:17], v[200:203], v[222:225], v[2:17]
	v_fma_f32 v136, v128, v140, v238
	s_cmp_eq_u64 s[0:1], 0
	s_cbranch_scc1 .Lmla_w2b
	s_waitcnt vmcnt(3)
	s_branch .Lmla_w3b

; template <int DQK>
; DI void attn_tile(const u16* __restrict__ q, int ldq, int qpos0, const Seg& s0, const Seg& s1, int nseg, bool has_sink,
;                   float sinkl2, u16* __restrict__ out, int ldo, char* lds) {
;     ...
;     __syncthreads();
;     ATT_STOREX(kreg0, kreg1, vreg0);
;     __syncthreads();
;     if (i + 2 < NT) ATT_LOADX(i + 2, kreg0, kreg1, vreg0);
.Lmla_w3b:
	ds_write_b128 v121, v[90:93]
	s_and_saveexec_b64 s[4:5], s[0:1]
	ds_write_b128 v129, v[94:97]
	s_or_b64 exec, exec, s[4:5]
	s_cmp_gt_u32 s27, 64
	ds_write_b128 v132, v[110:113] offset:46080
	s_waitcnt lgkmcnt(0)
	s_barrier
	s_cbranch_scc1 .LBB0_602
	s_cmp_eq_u32 s27, 60
	s_cbranch_scc0 .Lmla_o_noswk
	s_sub_u32 s16, s10, s14
	s_lshr_b32 s16, s16, 6
	s_sub_u32 s16, s16, 0x1000
	v_lshrrev_b32_e32 v34, 7, v236
	v_mul_lo_u32 v34, v34, s16
	v_add_u32_e32 v138, v138, v34
	v_lshrrev_b32_e32 v34, 7, v237
	v_mul_lo_u32 v34, v34, s16
	v_add_u32_e32 v142, v142, v34
.Lmla_o_noswk:
	s_cmp_eq_u32 s27, 62
	s_cbranch_scc0 .Lmla_o_noswv
	s_sub_u32 s16, s10, s14
	s_lshr_b32 s16, s16, 6
	s_sub_u32 s16, s16, 0x1000
	s_mul_i32 s17, s16, 0x480
	v_add_u32_e32 v235, s17, v235
.Lmla_o_noswv:
	v_add_u32_e32 v138, v138, v236
	v_add_u32_e32 v142, v142, v237
	v_add_u32_e32 v235, 0x24000, v235
	global_load_dwordx4 v[90:93], v138, s[84:85]
	s_and_saveexec_b64 s[16:17], s[0:1]
	global_load_dwordx4 v[94:97], v142, s[84:85]
	s_or_b64 exec, exec, s[16:17]
	global_load_dwordx4 v[110:113], v235, s[84:85]
	s_branch .LBB0_602
